# v19: v18 plus the rare O-rescale block moved out of line so the common path falls through into the PV MFMAs (no taken branch per sub-tile)
# baseline (speedup 1.0000x reference)
; __device__ __forceinline__ void att_softmax(f32x16& s, float sc, float& m, float& l, f32x16 (&o)[4], bf16x8& pf0, bf16x8& pf1) {
;     ...
;     const float alpha = __builtin_amdgcn_exp2f(m - msafe);
;     m = mnew;
;     float rs0 = 0.f, rs1 = 0.f;
; #pragma unroll
;     for (int i = 0; i < 16; i += 2) { s[i] = __builtin_amdgcn_exp2f(s[i] * sc - msafe); s[i + 1] = __builtin_amdgcn_exp2f(s[i + 1] * sc - msafe); rs0 += s[i]; rs1 += s[i + 1]; }
;     l = l * alpha + (rs0 + rs1);
;     if (__builtin_amdgcn_ballot_w64(alpha != 1.0f) != 0ull) {
; #pragma unroll
;         for (int db = 0; db < 4; ++db) o[db] = o[db] * alpha; }
.LBB0_118:
	v_fma_f32 v66, v66, s5, -v234
	v_fma_f32 v67, v67, s5, -v234
	v_exp_f32_e32 v66, v66
	v_exp_f32_e32 v67, v67
	v_fma_f32 v68, v68, s5, -v234
	v_fma_f32 v69, v69, s5, -v234
	v_exp_f32_e32 v68, v68
	v_exp_f32_e32 v69, v69
	v_fma_f32 v70, v70, s5, -v234
	v_fma_f32 v71, v71, s5, -v234
	v_exp_f32_e32 v70, v70
	v_exp_f32_e32 v71, v71
	v_fma_f32 v72, v72, s5, -v234
	v_fma_f32 v73, v73, s5, -v234
	v_exp_f32_e32 v72, v72
	v_exp_f32_e32 v73, v73
	v_fma_f32 v74, v74, s5, -v234
	v_fma_f32 v75, v75, s5, -v234
	v_add_f32_e32 v200, 0, v66
	v_add_f32_e32 v201, 0, v67
	v_exp_f32_e32 v74, v74
	v_exp_f32_e32 v75, v75
	v_fma_f32 v76, v76, s5, -v234
	v_fma_f32 v77, v77, s5, -v234
	v_add_f32_e32 v200, v68, v200
	v_add_f32_e32 v201, v69, v201
	v_exp_f32_e32 v76, v76
	v_exp_f32_e32 v77, v77
	v_fma_f32 v78, v78, s5, -v234
	v_fma_f32 v79, v79, s5, -v234
	v_add_f32_e32 v200, v70, v200
	v_add_f32_e32 v201, v71, v201
	v_exp_f32_e32 v78, v78
	v_exp_f32_e32 v79, v79
	v_fma_f32 v80, v80, s5, -v234
	v_fma_f32 v81, v81, s5, -v234
	v_add_f32_e32 v200, v72, v200
	v_add_f32_e32 v201, v73, v201
	v_exp_f32_e32 v80, v80
	v_exp_f32_e32 v81, v81
	v_add_f32_e32 v200, v74, v200
	v_add_f32_e32 v201, v75, v201
	v_add_f32_e32 v200, v76, v200
	v_add_f32_e32 v201, v77, v201
	v_add_f32_e32 v200, v78, v200
	v_add_f32_e32 v201, v79, v201
	v_add_f32_e32 v200, v80, v200
	v_add_f32_e32 v201, v81, v201
	v_add_f32_e32 v234, v200, v201
	v_fmac_f32_e32 v234, v233, v224
	s_cmp_ge_i32 s85, s67
	v_cvt_pk_bf16_f32 v66, v66, v67
	v_cvt_pk_bf16_f32 v67, v68, v69
	v_cvt_pk_bf16_f32 v68, v70, v71
	v_cvt_pk_bf16_f32 v69, v72, v73
	v_cvt_pk_bf16_f32 v70, v74, v75
	v_cvt_pk_bf16_f32 v71, v76, v77
	v_cvt_pk_bf16_f32 v72, v78, v79
	v_cvt_pk_bf16_f32 v73, v80, v81
	v_cmp_neq_f32_e32 vcc, 1.0, v224
	s_cbranch_vccnz .Lresc_do_1

; __device__ __forceinline__ void att_softmax(f32x16& s, float sc, float& m, float& l, f32x16 (&o)[4], bf16x8& pf0, bf16x8& pf1) {
;     ...
;     const float alpha = __builtin_amdgcn_exp2f(m - msafe);
;     m = mnew;
;     float rs0 = 0.f, rs1 = 0.f;
; #pragma unroll
;     for (int i = 0; i < 16; i += 2) { s[i] = __builtin_amdgcn_exp2f(s[i] * sc - msafe); s[i + 1] = __builtin_amdgcn_exp2f(s[i + 1] * sc - msafe); rs0 += s[i]; rs1 += s[i + 1]; }
;     l = l * alpha + (rs0 + rs1);
;     if (__builtin_amdgcn_ballot_w64(alpha != 1.0f) != 0ull) {
; #pragma unroll
;         for (int db = 0; db < 4; ++db) o[db] = o[db] * alpha; }
.LBB0_125:
	v_fma_f32 v66, v66, s5, -v233
	v_fma_f32 v67, v67, s5, -v233
	v_exp_f32_e32 v66, v66
	v_exp_f32_e32 v67, v67
	v_fma_f32 v68, v68, s5, -v233
	v_fma_f32 v69, v69, s5, -v233
	v_exp_f32_e32 v68, v68
	v_exp_f32_e32 v69, v69
	v_fma_f32 v70, v70, s5, -v233
	v_fma_f32 v71, v71, s5, -v233
	v_exp_f32_e32 v70, v70
	v_exp_f32_e32 v71, v71
	v_fma_f32 v72, v72, s5, -v233
	v_fma_f32 v73, v73, s5, -v233
	v_exp_f32_e32 v72, v72
	v_exp_f32_e32 v73, v73
	v_fma_f32 v74, v74, s5, -v233
	v_fma_f32 v75, v75, s5, -v233
	v_add_f32_e32 v200, 0, v66
	v_add_f32_e32 v201, 0, v67
	v_exp_f32_e32 v74, v74
	v_exp_f32_e32 v75, v75
	v_fma_f32 v76, v76, s5, -v233
	v_fma_f32 v77, v77, s5, -v233
	v_add_f32_e32 v200, v68, v200
	v_add_f32_e32 v201, v69, v201
	v_exp_f32_e32 v76, v76
	v_exp_f32_e32 v77, v77
	v_fma_f32 v78, v78, s5, -v233
	v_fma_f32 v79, v79, s5, -v233
	v_add_f32_e32 v200, v70, v200
	v_add_f32_e32 v201, v71, v201
	v_exp_f32_e32 v78, v78
	v_exp_f32_e32 v79, v79
	v_fma_f32 v80, v80, s5, -v233
	v_fma_f32 v81, v81, s5, -v233
	v_add_f32_e32 v200, v72, v200
	v_add_f32_e32 v201, v73, v201
	v_exp_f32_e32 v80, v80
	v_exp_f32_e32 v81, v81
	v_add_f32_e32 v200, v74, v200
	v_add_f32_e32 v201, v75, v201
	v_add_f32_e32 v200, v76, v200
	v_add_f32_e32 v201, v77, v201
	v_add_f32_e32 v200, v78, v200
	v_add_f32_e32 v201, v79, v201
	v_add_f32_e32 v200, v80, v200
	v_add_f32_e32 v201, v81, v201
	v_add_f32_e32 v200, v200, v201
	v_fmac_f32_e32 v200, v234, v224
	v_cvt_pk_bf16_f32 v66, v66, v67
	v_cvt_pk_bf16_f32 v67, v68, v69
	v_cvt_pk_bf16_f32 v68, v70, v71
	v_cvt_pk_bf16_f32 v69, v72, v73
	v_cvt_pk_bf16_f32 v70, v74, v75
	v_cvt_pk_bf16_f32 v71, v76, v77
	v_cvt_pk_bf16_f32 v72, v78, v79
	v_cvt_pk_bf16_f32 v73, v80, v81
	v_cmp_neq_f32_e32 vcc, 1.0, v224
	s_cbranch_vccnz .Lresc_do_2

; __device__ __forceinline__ void att_softmax(f32x16& s, float sc, float& m, float& l, f32x16 (&o)[4], bf16x8& pf0, bf16x8& pf1) {
;     ...
;     if (__builtin_amdgcn_ballot_w64(alpha != 1.0f) != 0ull) {
; #pragma unroll
;         for (int db = 0; db < 4; ++db) o[db] = o[db] * alpha; }
.Lresc_do_2:
	v_pk_mul_f32 v[64:65], v[64:65], v[224:225] op_sel_hi:[1,0]
	v_pk_mul_f32 v[62:63], v[62:63], v[224:225] op_sel_hi:[1,0]
	v_pk_mul_f32 v[60:61], v[60:61], v[224:225] op_sel_hi:[1,0]
	v_pk_mul_f32 v[58:59], v[58:59], v[224:225] op_sel_hi:[1,0]
	v_pk_mul_f32 v[56:57], v[56:57], v[224:225] op_sel_hi:[1,0]
	v_pk_mul_f32 v[54:55], v[54:55], v[224:225] op_sel_hi:[1,0]
	v_pk_mul_f32 v[52:53], v[52:53], v[224:225] op_sel_hi:[1,0]
	v_pk_mul_f32 v[50:51], v[50:51], v[224:225] op_sel_hi:[1,0]
	v_pk_mul_f32 v[48:49], v[48:49], v[224:225] op_sel_hi:[1,0]
	v_pk_mul_f32 v[46:47], v[46:47], v[224:225] op_sel_hi:[1,0]
	v_pk_mul_f32 v[44:45], v[44:45], v[224:225] op_sel_hi:[1,0]
	v_pk_mul_f32 v[42:43], v[42:43], v[224:225] op_sel_hi:[1,0]
	v_pk_mul_f32 v[40:41], v[40:41], v[224:225] op_sel_hi:[1,0]
	v_pk_mul_f32 v[38:39], v[38:39], v[224:225] op_sel_hi:[1,0]
	v_pk_mul_f32 v[36:37], v[36:37], v[224:225] op_sel_hi:[1,0]
	v_pk_mul_f32 v[34:35], v[34:35], v[224:225] op_sel_hi:[1,0]
	v_pk_mul_f32 v[32:33], v[32:33], v[224:225] op_sel_hi:[1,0]
	v_pk_mul_f32 v[30:31], v[30:31], v[224:225] op_sel_hi:[1,0]
	v_pk_mul_f32 v[28:29], v[28:29], v[224:225] op_sel_hi:[1,0]
	v_pk_mul_f32 v[26:27], v[26:27], v[224:225] op_sel_hi:[1,0]
	v_pk_mul_f32 v[24:25], v[24:25], v[224:225] op_sel_hi:[1,0]
	v_pk_mul_f32 v[22:23], v[22:23], v[224:225] op_sel_hi:[1,0]
	v_pk_mul_f32 v[20:21], v[20:21], v[224:225] op_sel_hi:[1,0]
	v_pk_mul_f32 v[18:19], v[18:19], v[224:225] op_sel_hi:[1,0]
	v_pk_mul_f32 v[16:17], v[16:17], v[224:225] op_sel_hi:[1,0]
	v_pk_mul_f32 v[14:15], v[14:15], v[224:225] op_sel_hi:[1,0]
	v_pk_mul_f32 v[12:13], v[12:13], v[224:225] op_sel_hi:[1,0]
	v_pk_mul_f32 v[10:11], v[10:11], v[224:225] op_sel_hi:[1,0]
	v_pk_mul_f32 v[8:9], v[8:9], v[224:225] op_sel_hi:[1,0]
	v_pk_mul_f32 v[6:7], v[6:7], v[224:225] op_sel_hi:[1,0]
	v_pk_mul_f32 v[4:5], v[4:5], v[224:225] op_sel_hi:[1,0]
	v_pk_mul_f32 v[2:3], v[2:3], v[224:225] op_sel_hi:[1,0]
	s_nop 1
	s_branch .Lresc_skip_2

; __device__ __forceinline__ void att_softmax(f32x16& s, float sc, float& m, float& l, f32x16 (&o)[4], bf16x8& pf0, bf16x8& pf1) {
;     ...
;     const float alpha = __builtin_amdgcn_exp2f(m - msafe);
;     m = mnew;
;     float rs0 = 0.f, rs1 = 0.f;
; #pragma unroll
;     for (int i = 0; i < 16; i += 2) { s[i] = __builtin_amdgcn_exp2f(s[i] * sc - msafe); s[i + 1] = __builtin_amdgcn_exp2f(s[i + 1] * sc - msafe); rs0 += s[i]; rs1 += s[i + 1]; }
;     l = l * alpha + (rs0 + rs1);
;     if (__builtin_amdgcn_ballot_w64(alpha != 1.0f) != 0ull) {
; #pragma unroll
;         for (int db = 0; db < 4; ++db) o[db] = o[db] * alpha; }
.LBB0_146:
	v_fma_f32 v76, v245, s70, -v75
	v_fma_f32 v77, v240, s70, -v75
	v_exp_f32_e32 v76, v76
	v_exp_f32_e32 v77, v77
	v_fma_f32 v78, v238, s70, -v75
	v_fma_f32 v79, v235, s70, -v75
	v_exp_f32_e32 v78, v78
	v_exp_f32_e32 v79, v79
	v_fma_f32 v181, v234, s70, -v75
	v_fma_f32 v200, v233, s70, -v75
	v_exp_f32_e32 v181, v181
	v_exp_f32_e32 v200, v200
	v_fma_f32 v201, v232, s70, -v75
	v_fma_f32 v202, v231, s70, -v75
	v_exp_f32_e32 v201, v201
	v_exp_f32_e32 v202, v202
	v_fma_f32 v203, v230, s70, -v75
	v_fma_f32 v74, v74, s70, -v75
	v_add_f32_e32 v80, 0, v76
	v_add_f32_e32 v81, 0, v77
	v_exp_f32_e32 v203, v203
	v_exp_f32_e32 v74, v74
	v_add_f32_e32 v80, v78, v80
	v_add_f32_e32 v81, v79, v81
	v_add_f32_e32 v80, v181, v80
	v_add_f32_e32 v81, v200, v81
	v_fma_f32 v73, v73, s70, -v75
	v_fma_f32 v72, v72, s70, -v75
	v_add_f32_e32 v80, v201, v80
	v_add_f32_e32 v81, v202, v81
	v_exp_f32_e32 v208, v73
	v_exp_f32_e32 v209, v72
	v_fma_f32 v71, v71, s70, -v75
	v_fma_f32 v70, v70, s70, -v75
	v_add_f32_e32 v72, v203, v80
	v_add_f32_e32 v73, v74, v81
	v_exp_f32_e32 v80, v71
	v_exp_f32_e32 v81, v70
	v_fma_f32 v69, v69, s70, -v75
	v_fma_f32 v68, v68, s70, -v75
	v_exp_f32_e32 v69, v69
	v_exp_f32_e32 v210, v68
	v_add_f32_e32 v72, v208, v72
	v_add_f32_e32 v73, v209, v73
	v_add_f32_e32 v68, v80, v72
	v_add_f32_e32 v70, v81, v73
	v_add_f32_e32 v68, v69, v68
	v_add_f32_e32 v70, v210, v70
	v_add_f32_e32 v68, v68, v70
	v_fmac_f32_e32 v68, v227, v66
	v_cvt_pk_bf16_f32 v70, v76, v77
	v_cvt_pk_bf16_f32 v71, v78, v79
	v_cvt_pk_bf16_f32 v72, v181, v200
	v_cvt_pk_bf16_f32 v73, v201, v202
	v_cvt_pk_bf16_f32 v74, v203, v74
	v_cvt_pk_bf16_f32 v75, v208, v209
	v_cvt_pk_bf16_f32 v76, v80, v81
	v_cvt_pk_bf16_f32 v77, v69, v210
	v_cmp_neq_f32_e32 vcc, 1.0, v66
	s_cbranch_vccnz .Lresc_do_3

; __device__ __forceinline__ void att_softmax(f32x16& s, float sc, float& m, float& l, f32x16 (&o)[4], bf16x8& pf0, bf16x8& pf1) {
;     ...
;     if (__builtin_amdgcn_ballot_w64(alpha != 1.0f) != 0ull) {
; #pragma unroll
;         for (int db = 0; db < 4; ++db) o[db] = o[db] * alpha; }
.Lresc_do_3:
	v_pk_mul_f32 v[64:65], v[64:65], v[66:67] op_sel_hi:[1,0]
	v_pk_mul_f32 v[62:63], v[62:63], v[66:67] op_sel_hi:[1,0]
	v_pk_mul_f32 v[60:61], v[60:61], v[66:67] op_sel_hi:[1,0]
	v_pk_mul_f32 v[58:59], v[58:59], v[66:67] op_sel_hi:[1,0]
	v_pk_mul_f32 v[56:57], v[56:57], v[66:67] op_sel_hi:[1,0]
	v_pk_mul_f32 v[54:55], v[54:55], v[66:67] op_sel_hi:[1,0]
	v_pk_mul_f32 v[52:53], v[52:53], v[66:67] op_sel_hi:[1,0]
	v_pk_mul_f32 v[50:51], v[50:51], v[66:67] op_sel_hi:[1,0]
	v_pk_mul_f32 v[48:49], v[48:49], v[66:67] op_sel_hi:[1,0]
	v_pk_mul_f32 v[46:47], v[46:47], v[66:67] op_sel_hi:[1,0]
	v_pk_mul_f32 v[44:45], v[44:45], v[66:67] op_sel_hi:[1,0]
	v_pk_mul_f32 v[42:43], v[42:43], v[66:67] op_sel_hi:[1,0]
	v_pk_mul_f32 v[40:41], v[40:41], v[66:67] op_sel_hi:[1,0]
	v_pk_mul_f32 v[38:39], v[38:39], v[66:67] op_sel_hi:[1,0]
	v_pk_mul_f32 v[36:37], v[36:37], v[66:67] op_sel_hi:[1,0]
	v_pk_mul_f32 v[34:35], v[34:35], v[66:67] op_sel_hi:[1,0]
	v_pk_mul_f32 v[32:33], v[32:33], v[66:67] op_sel_hi:[1,0]
	v_pk_mul_f32 v[30:31], v[30:31], v[66:67] op_sel_hi:[1,0]
	v_pk_mul_f32 v[28:29], v[28:29], v[66:67] op_sel_hi:[1,0]
	v_pk_mul_f32 v[26:27], v[26:27], v[66:67] op_sel_hi:[1,0]
	v_pk_mul_f32 v[24:25], v[24:25], v[66:67] op_sel_hi:[1,0]
	v_pk_mul_f32 v[22:23], v[22:23], v[66:67] op_sel_hi:[1,0]
	v_pk_mul_f32 v[20:21], v[20:21], v[66:67] op_sel_hi:[1,0]
	v_pk_mul_f32 v[18:19], v[18:19], v[66:67] op_sel_hi:[1,0]
	v_pk_mul_f32 v[16:17], v[16:17], v[66:67] op_sel_hi:[1,0]
	v_pk_mul_f32 v[14:15], v[14:15], v[66:67] op_sel_hi:[1,0]
	v_pk_mul_f32 v[12:13], v[12:13], v[66:67] op_sel_hi:[1,0]
	v_pk_mul_f32 v[10:11], v[10:11], v[66:67] op_sel_hi:[1,0]
	v_pk_mul_f32 v[8:9], v[8:9], v[66:67] op_sel_hi:[1,0]
	v_pk_mul_f32 v[6:7], v[6:7], v[66:67] op_sel_hi:[1,0]
	v_pk_mul_f32 v[4:5], v[4:5], v[66:67] op_sel_hi:[1,0]
	v_pk_mul_f32 v[2:3], v[2:3], v[66:67] op_sel_hi:[1,0]
	s_nop 1
	s_branch .Lresc_skip_3

; __device__ __forceinline__ void att_softmax(f32x16& s, float sc, float& m, float& l, f32x16 (&o)[4], bf16x8& pf0, bf16x8& pf1) {
;     ...
;     const float alpha = __builtin_amdgcn_exp2f(m - msafe);
;     m = mnew;
;     float rs0 = 0.f, rs1 = 0.f;
; #pragma unroll
;     for (int i = 0; i < 16; i += 2) { s[i] = __builtin_amdgcn_exp2f(s[i] * sc - msafe); s[i + 1] = __builtin_amdgcn_exp2f(s[i + 1] * sc - msafe); rs0 += s[i]; rs1 += s[i + 1]; }
;     l = l * alpha + (rs0 + rs1);
;     if (__builtin_amdgcn_ballot_w64(alpha != 1.0f) != 0ull) {
; #pragma unroll
;         for (int db = 0; db < 4; ++db) o[db] = o[db] * alpha; }
.LBB0_278:
	v_fma_f32 v80, v80, s80, -v181
	v_exp_f32_e32 v136, v80
	v_fma_f32 v80, v81, s80, -v181
	v_exp_f32_e32 v81, v80
	v_fma_f32 v80, v82, s80, -v181
	v_exp_f32_e32 v137, v80
	v_fma_f32 v80, v83, s80, -v181
	v_exp_f32_e32 v83, v80
	v_fma_f32 v84, v84, s80, -v181
	v_fma_f32 v85, v85, s80, -v181
	v_exp_f32_e32 v84, v84
	v_exp_f32_e32 v85, v85
	v_fma_f32 v86, v86, s80, -v181
	v_fma_f32 v87, v87, s80, -v181
	v_exp_f32_e32 v86, v86
	v_exp_f32_e32 v87, v87
	v_fma_f32 v88, v88, s80, -v181
	v_fma_f32 v89, v89, s80, -v181
	v_exp_f32_e32 v88, v88
	v_exp_f32_e32 v89, v89
	v_fma_f32 v90, v90, s80, -v181
	v_fma_f32 v91, v91, s80, -v181
	v_add_f32_e32 v80, v137, v136
	v_add_f32_e32 v82, v83, v81
	v_exp_f32_e32 v90, v90
	v_exp_f32_e32 v91, v91
	v_fma_f32 v92, v92, s80, -v181
	v_fma_f32 v93, v93, s80, -v181
	v_add_f32_e32 v80, v84, v80
	v_add_f32_e32 v82, v85, v82
	v_exp_f32_e32 v92, v92
	v_exp_f32_e32 v93, v93
	v_fma_f32 v94, v94, s80, -v181
	v_fma_f32 v95, v95, s80, -v181
	v_add_f32_e32 v80, v86, v80
	v_add_f32_e32 v82, v87, v82
	v_exp_f32_e32 v94, v94
	v_exp_f32_e32 v95, v95
	v_add_f32_e32 v80, v88, v80
	v_add_f32_e32 v82, v89, v82
	v_add_f32_e32 v80, v90, v80
	v_add_f32_e32 v82, v91, v82
	v_add_f32_e32 v80, v92, v80
	v_add_f32_e32 v82, v93, v82
	v_add_f32_e32 v80, v94, v80
	v_add_f32_e32 v82, v95, v82
	v_add_f32_e32 v80, v80, v82
	v_fmac_f32_e32 v80, v219, v0
	v_cvt_pk_bf16_f32 v82, v136, v81
	v_cvt_pk_bf16_f32 v83, v137, v83
	v_cvt_pk_bf16_f32 v84, v84, v85
	v_cvt_pk_bf16_f32 v85, v86, v87
	v_cvt_pk_bf16_f32 v86, v88, v89
	v_cvt_pk_bf16_f32 v87, v90, v91
	v_cvt_pk_bf16_f32 v88, v92, v93
	v_cvt_pk_bf16_f32 v89, v94, v95
	v_cmp_neq_f32_e32 vcc, 1.0, v0
	s_cbranch_vccnz .Lresc_do_4

; __device__ __forceinline__ void att_softmax(f32x16& s, float sc, float& m, float& l, f32x16 (&o)[4], bf16x8& pf0, bf16x8& pf1) {
;     ...
;     if (__builtin_amdgcn_ballot_w64(alpha != 1.0f) != 0ull) {
; #pragma unroll
;         for (int db = 0; db < 4; ++db) o[db] = o[db] * alpha; }
.Lresc_do_4:
	v_pk_mul_f32 v[78:79], v[0:1], v[78:79] op_sel_hi:[0,1]
	v_pk_mul_f32 v[76:77], v[0:1], v[76:77] op_sel_hi:[0,1]
	v_pk_mul_f32 v[74:75], v[0:1], v[74:75] op_sel_hi:[0,1]
	v_pk_mul_f32 v[72:73], v[0:1], v[72:73] op_sel_hi:[0,1]
	v_pk_mul_f32 v[70:71], v[0:1], v[70:71] op_sel_hi:[0,1]
	v_pk_mul_f32 v[68:69], v[0:1], v[68:69] op_sel_hi:[0,1]
	v_pk_mul_f32 v[66:67], v[0:1], v[66:67] op_sel_hi:[0,1]
	v_pk_mul_f32 v[64:65], v[0:1], v[64:65] op_sel_hi:[0,1]
	v_pk_mul_f32 v[62:63], v[0:1], v[62:63] op_sel_hi:[0,1]
	v_pk_mul_f32 v[60:61], v[0:1], v[60:61] op_sel_hi:[0,1]
	v_pk_mul_f32 v[58:59], v[0:1], v[58:59] op_sel_hi:[0,1]
	v_pk_mul_f32 v[56:57], v[0:1], v[56:57] op_sel_hi:[0,1]
	v_pk_mul_f32 v[54:55], v[0:1], v[54:55] op_sel_hi:[0,1]
	v_pk_mul_f32 v[52:53], v[0:1], v[52:53] op_sel_hi:[0,1]
	v_pk_mul_f32 v[50:51], v[0:1], v[50:51] op_sel_hi:[0,1]
	v_pk_mul_f32 v[48:49], v[0:1], v[48:49] op_sel_hi:[0,1]
	v_pk_mul_f32 v[46:47], v[0:1], v[46:47] op_sel_hi:[0,1]
	v_pk_mul_f32 v[44:45], v[0:1], v[44:45] op_sel_hi:[0,1]
	v_pk_mul_f32 v[42:43], v[0:1], v[42:43] op_sel_hi:[0,1]
	v_pk_mul_f32 v[40:41], v[0:1], v[40:41] op_sel_hi:[0,1]
	v_pk_mul_f32 v[38:39], v[0:1], v[38:39] op_sel_hi:[0,1]
	v_pk_mul_f32 v[36:37], v[0:1], v[36:37] op_sel_hi:[0,1]
	v_pk_mul_f32 v[34:35], v[0:1], v[34:35] op_sel_hi:[0,1]
	v_pk_mul_f32 v[32:33], v[0:1], v[32:33] op_sel_hi:[0,1]
	v_pk_mul_f32 v[30:31], v[0:1], v[30:31] op_sel_hi:[0,1]
	v_pk_mul_f32 v[28:29], v[0:1], v[28:29] op_sel_hi:[0,1]
	v_pk_mul_f32 v[26:27], v[0:1], v[26:27] op_sel_hi:[0,1]
	v_pk_mul_f32 v[24:25], v[0:1], v[24:25] op_sel_hi:[0,1]
	v_pk_mul_f32 v[22:23], v[0:1], v[22:23] op_sel_hi:[0,1]
	v_pk_mul_f32 v[20:21], v[0:1], v[20:21] op_sel_hi:[0,1]
	v_pk_mul_f32 v[18:19], v[0:1], v[18:19] op_sel_hi:[0,1]
	v_pk_mul_f32 v[16:17], v[0:1], v[16:17] op_sel_hi:[0,1]
	s_nop 1
	s_branch .Lresc_skip_4

; __device__ __forceinline__ void att_softmax(f32x16& s, float sc, float& m, float& l, f32x16 (&o)[4], bf16x8& pf0, bf16x8& pf1) {
;     ...
;     const float alpha = __builtin_amdgcn_exp2f(m - msafe);
;     m = mnew;
;     float rs0 = 0.f, rs1 = 0.f;
; #pragma unroll
;     for (int i = 0; i < 16; i += 2) { s[i] = __builtin_amdgcn_exp2f(s[i] * sc - msafe); s[i + 1] = __builtin_amdgcn_exp2f(s[i + 1] * sc - msafe); rs0 += s[i]; rs1 += s[i + 1]; }
;     l = l * alpha + (rs0 + rs1);
;     if (__builtin_amdgcn_ballot_w64(alpha != 1.0f) != 0ull) {
; #pragma unroll
;         for (int db = 0; db < 4; ++db) o[db] = o[db] * alpha; }
.LBB0_304:
	v_fma_f32 v80, v80, s70, -v240
	v_fma_f32 v81, v81, s70, -v240
	v_exp_f32_e32 v80, v80
	v_exp_f32_e32 v81, v81
	v_fma_f32 v82, v82, s70, -v240
	v_fma_f32 v83, v83, s70, -v240
	v_exp_f32_e32 v82, v82
	v_exp_f32_e32 v83, v83
	v_fma_f32 v84, v84, s70, -v240
	v_fma_f32 v85, v85, s70, -v240
	v_exp_f32_e32 v84, v84
	v_exp_f32_e32 v85, v85
	v_fma_f32 v86, v86, s70, -v240
	v_fma_f32 v87, v87, s70, -v240
	v_exp_f32_e32 v86, v86
	v_exp_f32_e32 v87, v87
	v_fma_f32 v88, v88, s70, -v240
	v_fma_f32 v89, v89, s70, -v240
	v_exp_f32_e32 v88, v88
	v_exp_f32_e32 v89, v89
	v_fma_f32 v90, v90, s70, -v240
	v_fma_f32 v91, v91, s70, -v240
	v_add_f32_e32 v200, v82, v80
	v_add_f32_e32 v201, v83, v81
	v_exp_f32_e32 v90, v90
	v_exp_f32_e32 v91, v91
	v_fma_f32 v92, v92, s70, -v240
	v_fma_f32 v93, v93, s70, -v240
	v_add_f32_e32 v200, v84, v200
	v_add_f32_e32 v201, v85, v201
	v_exp_f32_e32 v92, v92
	v_exp_f32_e32 v93, v93
	v_fma_f32 v94, v94, s70, -v240
	v_fma_f32 v95, v95, s70, -v240
	v_add_f32_e32 v200, v86, v200
	v_add_f32_e32 v201, v87, v201
	v_exp_f32_e32 v94, v94
	v_exp_f32_e32 v95, v95
	v_add_f32_e32 v200, v88, v200
	v_add_f32_e32 v201, v89, v201
	v_add_f32_e32 v200, v90, v200
	v_add_f32_e32 v201, v91, v201
	v_add_f32_e32 v200, v92, v200
	v_add_f32_e32 v201, v93, v201
	v_add_f32_e32 v200, v94, v200
	v_add_f32_e32 v201, v95, v201
	v_add_f32_e32 v200, v200, v201
	v_fmac_f32_e32 v200, v227, v0
	v_cvt_pk_bf16_f32 v80, v80, v81
	v_cvt_pk_bf16_f32 v81, v82, v83
	v_cvt_pk_bf16_f32 v82, v84, v85
	v_cvt_pk_bf16_f32 v83, v86, v87
	v_cvt_pk_bf16_f32 v84, v88, v89
	v_cvt_pk_bf16_f32 v85, v90, v91
	v_cvt_pk_bf16_f32 v86, v92, v93
	v_cvt_pk_bf16_f32 v87, v94, v95
	v_cmp_neq_f32_e32 vcc, 1.0, v0
	s_cbranch_vccnz .Lresc_do_5

; __device__ __forceinline__ void att_softmax(f32x16& s, float sc, float& m, float& l, f32x16 (&o)[4], bf16x8& pf0, bf16x8& pf1) {
;     ...
;     if (__builtin_amdgcn_ballot_w64(alpha != 1.0f) != 0ull) {
; #pragma unroll
;         for (int db = 0; db < 4; ++db) o[db] = o[db] * alpha; }
.Lresc_do_5:
	v_pk_mul_f32 v[78:79], v[78:79], v[0:1] op_sel_hi:[1,0]
	v_pk_mul_f32 v[76:77], v[76:77], v[0:1] op_sel_hi:[1,0]
	v_pk_mul_f32 v[74:75], v[74:75], v[0:1] op_sel_hi:[1,0]
	v_pk_mul_f32 v[72:73], v[72:73], v[0:1] op_sel_hi:[1,0]
	v_pk_mul_f32 v[70:71], v[70:71], v[0:1] op_sel_hi:[1,0]
	v_pk_mul_f32 v[68:69], v[68:69], v[0:1] op_sel_hi:[1,0]
	v_pk_mul_f32 v[66:67], v[66:67], v[0:1] op_sel_hi:[1,0]
	v_pk_mul_f32 v[64:65], v[64:65], v[0:1] op_sel_hi:[1,0]
	v_pk_mul_f32 v[62:63], v[62:63], v[0:1] op_sel_hi:[1,0]
	v_pk_mul_f32 v[60:61], v[60:61], v[0:1] op_sel_hi:[1,0]
	v_pk_mul_f32 v[58:59], v[58:59], v[0:1] op_sel_hi:[1,0]
	v_pk_mul_f32 v[56:57], v[56:57], v[0:1] op_sel_hi:[1,0]
	v_pk_mul_f32 v[54:55], v[54:55], v[0:1] op_sel_hi:[1,0]
	v_pk_mul_f32 v[52:53], v[52:53], v[0:1] op_sel_hi:[1,0]
	v_pk_mul_f32 v[50:51], v[50:51], v[0:1] op_sel_hi:[1,0]
	v_pk_mul_f32 v[48:49], v[48:49], v[0:1] op_sel_hi:[1,0]
	v_pk_mul_f32 v[46:47], v[46:47], v[0:1] op_sel_hi:[1,0]
	v_pk_mul_f32 v[44:45], v[44:45], v[0:1] op_sel_hi:[1,0]
	v_pk_mul_f32 v[42:43], v[42:43], v[0:1] op_sel_hi:[1,0]
	v_pk_mul_f32 v[40:41], v[40:41], v[0:1] op_sel_hi:[1,0]
	v_pk_mul_f32 v[38:39], v[38:39], v[0:1] op_sel_hi:[1,0]
	v_pk_mul_f32 v[36:37], v[36:37], v[0:1] op_sel_hi:[1,0]
	v_pk_mul_f32 v[34:35], v[34:35], v[0:1] op_sel_hi:[1,0]
	v_pk_mul_f32 v[32:33], v[32:33], v[0:1] op_sel_hi:[1,0]
	v_pk_mul_f32 v[30:31], v[30:31], v[0:1] op_sel_hi:[1,0]
	v_pk_mul_f32 v[28:29], v[28:29], v[0:1] op_sel_hi:[1,0]
	v_pk_mul_f32 v[26:27], v[26:27], v[0:1] op_sel_hi:[1,0]
	v_pk_mul_f32 v[24:25], v[24:25], v[0:1] op_sel_hi:[1,0]
	v_pk_mul_f32 v[22:23], v[22:23], v[0:1] op_sel_hi:[1,0]
	v_pk_mul_f32 v[20:21], v[20:21], v[0:1] op_sel_hi:[1,0]
	v_pk_mul_f32 v[18:19], v[18:19], v[0:1] op_sel_hi:[1,0]
	v_pk_mul_f32 v[16:17], v[16:17], v[0:1] op_sel_hi:[1,0]
	s_nop 1
	s_branch .Lresc_skip_5

; __device__ __forceinline__ void att_softmax(f32x16& s, float sc, float& m, float& l, f32x16 (&o)[4], bf16x8& pf0, bf16x8& pf1) {
;     ...
;     const float alpha = __builtin_amdgcn_exp2f(m - msafe);
;     m = mnew;
;     float rs0 = 0.f, rs1 = 0.f;
; #pragma unroll
;     for (int i = 0; i < 16; i += 2) { s[i] = __builtin_amdgcn_exp2f(s[i] * sc - msafe); s[i + 1] = __builtin_amdgcn_exp2f(s[i + 1] * sc - msafe); rs0 += s[i]; rs1 += s[i + 1]; }
;     l = l * alpha + (rs0 + rs1);
;     if (__builtin_amdgcn_ballot_w64(alpha != 1.0f) != 0ull) {
; #pragma unroll
;         for (int db = 0; db < 4; ++db) o[db] = o[db] * alpha; }
.LBB0_313:
	v_fma_f32 v15, v15, s70, -v95
	v_fma_f32 v80, v80, s70, -v95
	v_exp_f32_e32 v15, v15
	v_exp_f32_e32 v80, v80
	v_fma_f32 v81, v81, s70, -v95
	v_fma_f32 v82, v82, s70, -v95
	v_exp_f32_e32 v81, v81
	v_exp_f32_e32 v82, v82
	v_fma_f32 v83, v83, s70, -v95
	v_fma_f32 v84, v84, s70, -v95
	v_exp_f32_e32 v83, v83
	v_exp_f32_e32 v84, v84
	v_fma_f32 v85, v85, s70, -v95
	v_fma_f32 v86, v86, s70, -v95
	v_exp_f32_e32 v85, v85
	v_exp_f32_e32 v86, v86
	v_fma_f32 v87, v87, s70, -v95
	v_fma_f32 v88, v88, s70, -v95
	v_exp_f32_e32 v87, v87
	v_exp_f32_e32 v88, v88
	v_fma_f32 v89, v89, s70, -v95
	v_fma_f32 v90, v90, s70, -v95
	v_add_f32_e32 v132, v81, v15
	v_add_f32_e32 v133, v82, v80
	v_exp_f32_e32 v89, v89
	v_exp_f32_e32 v90, v90
	v_fma_f32 v91, v91, s70, -v95
	v_fma_f32 v92, v92, s70, -v95
	v_add_f32_e32 v132, v83, v132
	v_add_f32_e32 v133, v84, v133
	v_exp_f32_e32 v91, v91
	v_exp_f32_e32 v92, v92
	v_fma_f32 v93, v93, s70, -v95
	v_fma_f32 v94, v94, s70, -v95
	v_add_f32_e32 v132, v85, v132
	v_add_f32_e32 v133, v86, v133
	v_exp_f32_e32 v93, v93
	v_exp_f32_e32 v94, v94
	v_add_f32_e32 v132, v87, v132
	v_add_f32_e32 v133, v88, v133
	v_add_f32_e32 v132, v89, v132
	v_add_f32_e32 v133, v90, v133
	v_add_f32_e32 v95, v91, v132
	v_add_f32_e32 v132, v92, v133
	v_add_f32_e32 v95, v93, v95
	v_add_f32_e32 v132, v94, v132
	v_add_f32_e32 v95, v95, v132
	v_fmac_f32_e32 v95, v227, v0
	v_cvt_pk_bf16_f32 v80, v15, v80
	v_cvt_pk_bf16_f32 v81, v81, v82
	v_cvt_pk_bf16_f32 v82, v83, v84
	v_cvt_pk_bf16_f32 v83, v85, v86
	v_cvt_pk_bf16_f32 v84, v87, v88
	v_cvt_pk_bf16_f32 v85, v89, v90
	v_cvt_pk_bf16_f32 v86, v91, v92
	v_cvt_pk_bf16_f32 v87, v93, v94
	v_cmp_neq_f32_e32 vcc, 1.0, v0
	s_cbranch_vccnz .Lresc_do_6
